# diff attention: one barrier per tile in the staggered loop; FoX keeps the compiled loop; static unit order; bias-table reuse
# speedup vs baseline: 1.0243x; 1.0059x over previous
; #define LAS __attribute__((address_space(3)))
; template <int DV, int NMAP>
; __device__ __forceinline__ void attn_unit(LAS unsigned char* lds, const bf16_t* U, bf16_t* MIX, const float* logf, int b, int h, int qb, float lam, float slope2, const float* gn, float outscale, const int tid) {
;     ...
;     LAS float* bias = (LAS float*)(lds + AT_BIAS);
;     {
;         const int n = q0 + QROWS;
;         if (NMAP == 1) {
;             LAS float* scan = (LAS float*)(lds + AT_SCAN);
;             LAS float* tots = (LAS float*)(lds + AT_K);
;             float v0 = 0.f, v1 = 0.f, v2 = 0.f, v3 = 0.f;
;             if (4 * tid < n) { const float* lp = logf + (rowbase + 4 * tid) * 8 + h; v0 = lp[0]; v1 = lp[8]; v2 = lp[16]; v3 = lp[24]; }
;             const float p1 = v0, p2 = v0 + v1, p3 = p2 + v2, tot = p3 + v3;
;             tots[tid] = tot;
;             __syncthreads();
;             float incl = 0.f, wsum = 0.f;
; #pragma unroll
;             for (int j4 = 0; j4 < 16; ++j4) { const f32x4 t = *(const LAS f32x4*)(tots + wid * 64 + 4 * j4);
; #pragma unroll
;                 for (int i = 0; i < 4; ++i) { wsum += t[i]; incl += (4 * j4 + i <= lane) ? t[i] : 0.f; } }
;             if (lane == 63) scan[wid] = wsum;
;             __syncthreads();
;             float wpre = 0.f;
;             for (int w = 0; w < wid; ++w) wpre += scan[w];
;             const float ex = wpre + incl - tot;
;             if (4 * tid < n) *(LAS f32x4*)(bias + 4 * tid) = (f32x4){-(ex + p1) * LOG2E, -(ex + p2) * LOG2E, -(ex + p3) * LOG2E, -(ex + tot) * LOG2E};
;         } else {
;             for (int s = tid; s < n; s += 512) bias[s] = slope2 * (float)s;
; __device__ __forceinline__ void attn_phase(const Args& a, int l, LAS unsigned char* lds, const int tid, const int rep) {
;     ...
;         if (i >= 1024u) break;
;         if (i < 512u) {
;             const int qb = 15 - (int)(i >> 5), bh = (int)(i & 31), b = bh >> 2, h = bh & 3;
;             const float slope2 = exp2f(-2.0f * (float)(h + 1)) * LOG2E;
;             attn_unit<128, 2>(lds, U, MIX, logf, b, h, qb, lam, slope2, gn, 1.0f - lam_init, tid);
;         } else {
;             const int j = (int)i - 512, qb = 7 - (j >> 6), bh = j & 63, b = bh >> 3, h = bh & 7;
;             attn_unit<64, 1>(lds, U, MIX, logf, b, h, qb, 0.f, 0.f, gn, 1.f, tid);
.Lat_disp:
	v_cmp_lt_u32_e32 vcc, s46, v0
	v_readfirstlane_b32 s27, v0
	s_cbranch_vccnz .LBB0_177
	s_cmpk_gt_u32 s27, 0x1ff
	s_cbranch_scc0 .LBB0_206
	s_not_b32 s20, s27
	s_lshl_b32 s20, s20, 2
	s_and_b32 s33, s20, 0xf00
	s_lshl_b32 s20, s27, 8
	s_add_i32 s37, s33, 0x100
	s_and_b32 s60, s27, 7
	v_readfirstlane_b32 s41, v188
	s_and_b32 s20, s20, 0x3800
	v_readlane_b32 s30, v255, 20
	s_ashr_i32 s40, s41, 6
	s_cmp_eq_u32 s30, 4
	s_cbranch_scc1 .Lfx_bias_done
	v_cmp_gt_i32_e32 vcc, s37, v124
	v_mov_b32_e32 v0, 0
	v_mov_b32_e32 v2, 0
	v_mov_b32_e32 v3, 0
	v_mov_b32_e32 v66, 0
	s_and_saveexec_b64 s[30:31], vcc
	s_cbranch_execz .LBB0_186
	v_lshl_add_u64 v[2:3], s[20:21], 0, v[124:125]
	v_lshlrev_b64 v[2:3], 5, v[2:3]
	v_lshl_add_u64 v[2:3], s[44:45], 0, v[2:3]
	s_lshl_b32 s62, s60, 2
	s_mov_b32 s63, s21
	v_lshl_add_u64 v[4:5], v[2:3], 0, s[62:63]
	global_load_dword v66, v[4:5], off
	global_load_dword v3, v[4:5], off offset:32
	global_load_dword v2, v[4:5], off offset:64
	global_load_dword v0, v[4:5], off offset:96

; template <int DV, int NMAP>
; __device__ __forceinline__ void attn_unit(LAS unsigned char* lds, const bf16_t* U, bf16_t* MIX, const float* logf, int b, int h, int qb, float lam, float slope2, const float* gn, float outscale, const int tid) {
;     ...
;     bf16x8 qr[4];
;     {
;         const bf16_t* qp = U + (rowbase + qrow0 + r32) * UW + qcol + map * 64 + hi * 8;
; #pragma unroll
;         for (int d0 = 0; d0 < 4; ++d0) qr[d0] = *(const bf16x8*)(qp + 16 * d0);
;     }
;     asm volatile("" : "+v"(qr[0]), "+v"(qr[1]), "+v"(qr[2]), "+v"(qr[3]));
;     const bf16_t* kg = U + (rowbase + lane) * UW + kcol + wid * 8;
;     const bf16_t* vg = U + (rowbase + 16 * (wid & 3) + (lane >> 2)) * UW + vcol + (wid >> 2) * 32 + (lane & 3) * 8;
;     const unsigned ldsb = (unsigned)(size_t)lds;
;     ...
;     __syncthreads();
;     AT_DMA(0, 0);
;     if (NT > 1) AT_DMA(1, 1);
;     const float m_run = bias[qrow0 + r32];
;     float l_run = 0.f;
;     f32x16 o[NDB];
; #pragma unroll
;     for (int d = 0; d < NDB; ++d)
; #pragma unroll
;         for (int r = 0; r < 16; ++r) o[d][r] = 0.f;
;     const int vofs = (4 * hi + ((lane & 15) >> 2)) * 64 + ((lane >> 4) & 1) * 32 + (lane & 3) * 8;
;     int st = 0, st2 = 2;
.Lfx_bias_done:
	s_lshl_b32 s36, s40, 5
	s_add_i32 s36, s36, s33
	s_lshr_b32 s37, s37, 6
	s_lshl_b32 s33, s60, 6
	s_ashr_i32 s30, s36, 31
	s_add_u32 s31, s36, s20
	v_or_b32_e32 v98, s31, v122
	v_mov_b64_e32 v[2:3], s[84:85]
	s_addc_u32 s61, s30, 0
	v_mad_u64_u32 v[2:3], s[30:31], v98, s87, v[2:3]
	v_mov_b32_e32 v0, 0x1800
	v_mad_i32_i24 v3, s61, v0, v3
	s_lshl_b32 s30, s60, 7
	s_mov_b32 s31, s21
	v_lshl_add_u64 v[2:3], v[2:3], 0, s[30:31]
	v_lshlrev_b32_e32 v0, 1, v126
	v_lshl_add_u64 v[2:3], v[2:3], 0, v[0:1]
	global_load_dwordx4 v[66:69], v[2:3], off offset:96
	global_load_dwordx4 v[70:73], v[2:3], off offset:64
	global_load_dwordx4 v[74:77], v[2:3], off offset:32
	global_load_dwordx4 v[78:81], v[2:3], off
	v_or_b32_e32 v0, s20, v123
	v_mul_u32_u24_e32 v0, 0xc00, v0
	v_lshlrev_b32_e32 v0, 1, v0
	v_lshl_add_u64 v[2:3], s[84:85], 0, v[0:1]
	s_lshl_b32 s60, s40, 3
	v_mov_b32_e32 v99, s61
	v_lshl_add_u64 v[2:3], v[2:3], 0, s[30:31]
	s_ashr_i32 s61, s60, 31
	v_lshl_add_u64 v[2:3], s[60:61], 1, v[2:3]
	s_mov_b64 s[60:61], 0x400
	v_lshl_add_u64 v[4:5], v[2:3], 0, s[60:61]
	s_bfe_u32 s60, s41, 0x20006
	v_lshl_or_b32 v0, s60, 4, v127
	v_or_b32_e32 v0, s20, v0
	v_mul_u32_u24_e32 v0, 0xc00, v0
	v_lshlrev_b32_e32 v0, 1, v0
	v_lshl_add_u64 v[6:7], s[84:85], 0, v[0:1]
	s_ashr_i32 s41, s41, 8
	v_lshl_add_u64 v[6:7], v[6:7], 0, s[30:31]
	s_lshl_b32 s30, s41, 5
	s_ashr_i32 s31, s30, 31
	s_mul_i32 s61, s40, 0x420
	v_lshl_add_u64 v[6:7], s[30:31], 1, v[6:7]
	s_add_i32 s20, s61, s49
	s_lshl_b32 s31, s60, 10
	v_lshlrev_b32_e32 v0, 1, v128
	v_lshl_add_u64 v[6:7], v[6:7], 0, v[0:1]
	v_lshl_add_u64 v[8:9], v[6:7], 0, s[50:51]
	v_or_b32_e32 v0, s36, v122
	v_mov_b32_e32 v105, 0
	s_or_b32 s60, s36, 31
	s_mov_b32 s64, 0
	v_mov_b32_e32 v106, v142
	s_mov_b32 s62, 0
	v_mov_b32_e32 v10, v105
	v_mov_b32_e32 v11, v105
	v_mov_b32_e32 v12, v105
	v_mov_b32_e32 v13, v105
	v_mov_b32_e32 v14, v105
	v_mov_b32_e32 v15, v105
	v_mov_b32_e32 v16, v105
	v_mov_b32_e32 v17, v105
	v_mov_b32_e32 v18, 0
	v_mov_b32_e32 v19, v105
	v_mov_b32_e32 v20, v105
	v_mov_b32_e32 v21, v105
	v_mov_b32_e32 v22, v105
	v_mov_b32_e32 v23, v105
	v_mov_b32_e32 v24, v105
	v_mov_b32_e32 v25, v105
	v_mov_b32_e32 v26, v105
	v_mov_b32_e32 v27, v105
	v_mov_b32_e32 v28, v105
	v_mov_b32_e32 v29, v105
	v_mov_b32_e32 v30, v105
	v_mov_b32_e32 v31, v105
	v_mov_b32_e32 v32, v105
	v_mov_b32_e32 v33, v105
	s_waitcnt vmcnt(0)
	s_waitcnt lgkmcnt(0)
	s_barrier
	s_mov_b32 s30, m0
	s_mov_b32 m0, s20
	s_nop 0
	global_load_lds_dwordx4 v[4:5], off
	s_mov_b32 m0, s30
	s_lshl_b32 s30, s41, 12
	s_or_b32 s30, s31, s30
	s_add_i32 s41, s30, 0
	s_add_i32 s40, s41, 0x8400
	s_mov_b32 s30, m0
	s_mov_b32 m0, s40
	s_nop 0
	global_load_lds_dwordx4 v[8:9], off
	s_mov_b32 m0, s30
	s_mov_b64 s[30:31], 0x60400
	v_lshl_add_u64 v[4:5], v[2:3], 0, s[30:31]
	s_add_i32 s30, s61, 0
	s_addk_i32 s30, 0x4200
	s_mov_b32 s31, m0
	s_mov_b32 m0, s30
	s_nop 0
	global_load_lds_dwordx4 v[4:5], off
	s_mov_b32 m0, s31
	s_mov_b64 s[30:31], 0x60800
	v_lshl_add_u64 v[4:5], v[6:7], 0, s[30:31]
	s_add_i32 s41, s41, 0xa400
	s_mov_b32 s30, m0
	s_mov_b32 m0, s41
	s_nop 0
	global_load_lds_dwordx4 v[4:5], off
	s_mov_b32 m0, s30
	v_lshl_add_u32 v4, v0, 2, 0
	ds_read_b32 v104, v4
	s_mov_b64 s[30:31], 0xc0800
	v_lshl_add_u64 v[100:101], v[6:7], 0, s[30:31]
	s_mov_b64 s[30:31], 0xc0400
	s_mov_b32 s41, 2
	v_lshl_add_u64 v[102:103], v[2:3], 0, s[30:31]
	s_mov_b32 s61, 63
	v_mov_b32_e32 v2, 0
	v_mov_b32_e32 v3, v105
	v_mov_b32_e32 v4, v105
	v_mov_b32_e32 v5, v105
	v_mov_b32_e32 v6, v105
	v_mov_b32_e32 v7, v105
	v_mov_b32_e32 v8, v105
	v_mov_b32_e32 v9, v105
	s_add_i32 s63, s64, 1
	s_cmp_ge_u32 s63, s37
	s_mov_b64 s[30:31], -1
	s_cbranch_scc1 .LBB0_197

; template <int DV, int NMAP>
; __device__ __forceinline__ void attn_unit(LAS unsigned char* lds, const bf16_t* U, bf16_t* MIX, const float* logf, int b, int h, int qb, float lam, float slope2, const float* gn, float outscale, const int tid) {
;     ...
;     const float m_run = bias[qrow0 + r32];
;     float l_run = 0.f;
;     f32x16 o[NDB];
; #pragma unroll
;     for (int d = 0; d < NDB; ++d)
; #pragma unroll
;         for (int r = 0; r < 16; ++r) o[d][r] = 0.f;
;     const int vofs = (4 * hi + ((lane & 15) >> 2)) * 64 + ((lane >> 4) & 1) * 32 + (lane & 3) * 8;
;     int st = 0, st2 = 2;
;     for (int t = 0; t < NT; ++t) {
;         if (t + 1 < NT) { if (PER == 2) asm volatile("s_waitcnt vmcnt(2)\n\ts_barrier" ::: "memory"); else asm volatile("s_waitcnt vmcnt(4)\n\ts_barrier" ::: "memory"); }
.Ldf_pro2:
	ds_read_b32 v149, v121
	v_mov_b32_e32 v2, 0
	v_mov_b32_e32 v3, 0
	v_mov_b32_e32 v4, 0
	v_mov_b32_e32 v5, 0
	v_mov_b32_e32 v6, 0
	v_mov_b32_e32 v7, 0
	v_mov_b32_e32 v8, 0
	v_mov_b32_e32 v9, 0
	v_mov_b32_e32 v10, 0
	v_mov_b32_e32 v11, 0
	v_mov_b32_e32 v12, 0
	v_mov_b32_e32 v13, 0
	v_mov_b32_e32 v14, 0
	v_mov_b32_e32 v15, 0
	v_mov_b32_e32 v16, 0
	v_mov_b32_e32 v17, 0
	v_mov_b32_e32 v18, 0
	v_mov_b32_e32 v19, 0
	v_mov_b32_e32 v20, 0
	v_mov_b32_e32 v21, 0
	v_mov_b32_e32 v22, 0
	v_mov_b32_e32 v23, 0
	v_mov_b32_e32 v24, 0
	v_mov_b32_e32 v25, 0
	v_mov_b32_e32 v26, 0
	v_mov_b32_e32 v27, 0
	v_mov_b32_e32 v28, 0
	v_mov_b32_e32 v29, 0
	v_mov_b32_e32 v30, 0
	v_mov_b32_e32 v31, 0
	v_mov_b32_e32 v32, 0
	v_mov_b32_e32 v33, 0
	v_mov_b32_e32 v34, 0
	v_mov_b32_e32 v35, 0
	v_mov_b32_e32 v36, 0
	v_mov_b32_e32 v37, 0
	v_mov_b32_e32 v38, 0
	v_mov_b32_e32 v39, 0
	v_mov_b32_e32 v40, 0
	v_mov_b32_e32 v41, 0
	v_mov_b32_e32 v42, 0
	v_mov_b32_e32 v43, 0
	v_mov_b32_e32 v44, 0
	v_mov_b32_e32 v45, 0
	v_mov_b32_e32 v46, 0
	v_mov_b32_e32 v47, 0
	v_mov_b32_e32 v48, 0
	v_mov_b32_e32 v49, 0
	v_mov_b32_e32 v50, 0
	v_mov_b32_e32 v51, 0
	v_mov_b32_e32 v52, 0
	v_mov_b32_e32 v53, 0
	v_mov_b32_e32 v54, 0
	v_mov_b32_e32 v55, 0
	v_mov_b32_e32 v56, 0
	v_mov_b32_e32 v57, 0
	v_mov_b32_e32 v58, 0
	v_mov_b32_e32 v59, 0
	v_mov_b32_e32 v60, 0
	v_mov_b32_e32 v61, 0
	v_mov_b32_e32 v62, 0
	v_mov_b32_e32 v63, 0
	v_mov_b32_e32 v64, 0
	v_mov_b32_e32 v65, 0
	s_cmp_gt_u32 s63, 2
	s_cbranch_scc1 .Ldf_w0
	s_waitcnt vmcnt(0)
	s_branch .Ldf_w0d

; template <int DV, int NMAP>
; __device__ __forceinline__ void attn_unit(LAS unsigned char* lds, const bf16_t* U, bf16_t* MIX, const float* logf, int b, int h, int qb, float lam, float slope2, const float* gn, float outscale, const int tid) {
;     ...
;     for (int t = 0; t < NT; ++t) {
;         if (t + 1 < NT) { if (PER == 2) asm volatile("s_waitcnt vmcnt(2)\n\ts_barrier" ::: "memory"); else asm volatile("s_waitcnt vmcnt(4)\n\ts_barrier" ::: "memory"); }
;         else asm volatile("s_waitcnt vmcnt(0)\n\ts_barrier" ::: "memory");
;         if (t + 2 < NT) AT_DMA(t + 2, st2);
.Ldf_w0d:
	s_barrier
	s_cmp_eq_u32 s60, 0
	s_cbranch_scc1 .Ldf_P
	s_barrier
	s_mov_b32 s30, 3
	s_cmp_ge_u32 s30, s63
	s_cbranch_scc1 .Ldf_P
	s_and_b32 s30, s30, 3
	s_mul_i32 s31, s30, 0x4200
	s_add_i32 s31, s31, s64
	s_lshl_b32 s20, s30, 14
	s_add_i32 s20, s20, s66
	s_mov_b32 m0, s31
	v_lshl_add_u64 v[116:117], v[136:137], 0, s[24:25]
	global_load_lds_dwordx4 v[136:137], off
	s_add_i32 m0, s31, 0x2100
	v_lshl_add_u64 v[136:137], v[136:137], 0, s[28:29]
	global_load_lds_dwordx4 v[116:117], off
	s_mov_b32 m0, s20
	v_lshl_add_u64 v[116:117], v[138:139], 0, s[24:25]
	global_load_lds_dwordx4 v[138:139], off
	s_add_i32 m0, s20, 0x400
	v_lshl_add_u64 v[138:139], v[138:139], 0, s[28:29]
	global_load_lds_dwordx4 v[116:117], off

; __device__ __forceinline__ unsigned pk_bf16(float lo, float hi) { return pg8::cvt_pk_bf16(lo, hi); }
; __device__ __forceinline__ s16x4 vtr(const LAS unsigned char* p) { typedef short v4i16_t __attribute__((ext_vector_type(4))); return __builtin_bit_cast(s16x4, __builtin_amdgcn_ds_read_tr16_b64_v4i16((LAS v4i16_t*)p)); }
; template <int DV, int NMAP>
; __device__ __forceinline__ void attn_unit(LAS unsigned char* lds, const bf16_t* U, bf16_t* MIX, const float* logf, int b, int h, int qb, float lam, float slope2, const float* gn, float outscale, const int tid) {
;     ...
;             s16x4 lo[2][4], hh[2][4];
; #pragma unroll
;             for (int e = 0; e < 2; ++e)
; #pragma unroll
;                 for (int s = 0; s < 4; ++s) { lo[e][s] = vtr(Vb + e * 4096 + s * 1024); hh[e][s] = vtr(Vb + e * 4096 + s * 1024 + 512); }
;             __builtin_amdgcn_sched_barrier(0);
;             {
;                 float s0 = 0.f, s1 = 0.f, s2 = 0.f, s3 = 0.f;
; #pragma unroll
;                 for (int r = 0; r < 16; r += 2) { p0[r] = __builtin_amdgcn_exp2f(p0[r] - m_run); p0[r + 1] = __builtin_amdgcn_exp2f(p0[r + 1] - m_run); p1[r] = __builtin_amdgcn_exp2f(p1[r] - m_run); p1[r + 1] = __builtin_amdgcn_exp2f(p1[r + 1] - m_run);
;                     s0 += p0[r]; s1 += p0[r + 1]; s2 += p1[r]; s3 += p1[r + 1]; }
;                 l_run += (s0 + s1) + (s2 + s3);
;             }
;             bf16x8 pk[4];
;             {
;                 u32x4 w;
;                 w.x = pk_bf16(p0[0], p0[1]); w.y = pk_bf16(p0[2], p0[3]); w.z = pk_bf16(p0[4], p0[5]); w.w = pk_bf16(p0[6], p0[7]); pk[0] = __builtin_bit_cast(bf16x8, w);
;                 w.x = pk_bf16(p0[8], p0[9]); w.y = pk_bf16(p0[10], p0[11]); w.z = pk_bf16(p0[12], p0[13]); w.w = pk_bf16(p0[14], p0[15]); pk[1] = __builtin_bit_cast(bf16x8, w);
;                 w.x = pk_bf16(p1[0], p1[1]); w.y = pk_bf16(p1[2], p1[3]); w.z = pk_bf16(p1[4], p1[5]); w.w = pk_bf16(p1[6], p1[7]); pk[2] = __builtin_bit_cast(bf16x8, w);
;                 w.x = pk_bf16(p1[8], p1[9]); w.y = pk_bf16(p1[10], p1[11]); w.z = pk_bf16(p1[12], p1[13]); w.w = pk_bf16(p1[14], p1[15]); pk[3] = __builtin_bit_cast(bf16x8, w);
;             }
.Ldf_P_nomask:
	s_cmp_lg_u32 s60, 0
	s_cbranch_scc1 .Ldf_loop
	s_barrier
.Ldf_loop:
	s_cmp_gt_u32 s37, s40
	s_cbranch_scc1 .Ldf_A_skip
	s_and_b32 s30, s37, 3
	s_lshl_b32 s30, s30, 14
	s_add_i32 s30, s30, 0x12900
	v_add_u32_e32 v119, s30, v141
	ds_read_b64_tr_b16 v[152:153], v119
	ds_read_b64_tr_b16 v[154:155], v119 offset:2048
	ds_read_b64_tr_b16 v[156:157], v119 offset:4096
	ds_read_b64_tr_b16 v[158:159], v119 offset:6144
	ds_read_b64_tr_b16 v[160:161], v119 offset:8192
	ds_read_b64_tr_b16 v[162:163], v119 offset:10240
	ds_read_b64_tr_b16 v[164:165], v119 offset:12288
	ds_read_b64_tr_b16 v[166:167], v119 offset:14336
	ds_read_b64_tr_b16 v[168:169], v119 offset:512
	ds_read_b64_tr_b16 v[170:171], v119 offset:2560
	ds_read_b64_tr_b16 v[172:173], v119 offset:4608
	ds_read_b64_tr_b16 v[174:175], v119 offset:6656
	ds_read_b64_tr_b16 v[176:177], v119 offset:8704
	ds_read_b64_tr_b16 v[178:179], v119 offset:10752
	ds_read_b64_tr_b16 v[190:191], v119 offset:12800
	ds_read_b64_tr_b16 v[192:193], v119 offset:14848
	ds_read_b64_tr_b16 v[194:195], v119 offset:1024
	ds_read_b64_tr_b16 v[196:197], v119 offset:3072
	ds_read_b64_tr_b16 v[198:199], v119 offset:5120
	ds_read_b64_tr_b16 v[200:201], v119 offset:7168
	ds_read_b64_tr_b16 v[234:235], v119 offset:9216
	ds_read_b64_tr_b16 v[236:237], v119 offset:11264
	ds_read_b64_tr_b16 v[238:239], v119 offset:13312
	ds_read_b64_tr_b16 v[240:241], v119 offset:15360
	v_sub_f32_e32 v82, v82, v149
	v_sub_f32_e32 v66, v66, v149
	v_sub_f32_e32 v83, v83, v149
	v_exp_f32_e32 v82, v82
	v_sub_f32_e32 v67, v67, v149
	v_exp_f32_e32 v66, v66
	v_sub_f32_e32 v84, v84, v149
	v_exp_f32_e32 v83, v83
	v_sub_f32_e32 v68, v68, v149
	v_exp_f32_e32 v67, v67
	v_sub_f32_e32 v85, v85, v149
	v_exp_f32_e32 v84, v84
	v_sub_f32_e32 v69, v69, v149
	v_exp_f32_e32 v68, v68
	v_sub_f32_e32 v86, v86, v149
	v_exp_f32_e32 v85, v85
	v_sub_f32_e32 v70, v70, v149
	v_exp_f32_e32 v69, v69
	v_sub_f32_e32 v87, v87, v149
	v_exp_f32_e32 v86, v86
	v_sub_f32_e32 v71, v71, v149
	v_exp_f32_e32 v70, v70
	v_sub_f32_e32 v88, v88, v149
	v_exp_f32_e32 v87, v87
	v_sub_f32_e32 v72, v72, v149
	v_exp_f32_e32 v71, v71
	v_sub_f32_e32 v89, v89, v149
	v_exp_f32_e32 v88, v88
	v_sub_f32_e32 v73, v73, v149
	v_exp_f32_e32 v72, v72
	v_sub_f32_e32 v90, v90, v149
	v_exp_f32_e32 v89, v89
	v_sub_f32_e32 v74, v74, v149
	v_exp_f32_e32 v73, v73
	v_sub_f32_e32 v91, v91, v149
	v_exp_f32_e32 v90, v90
	v_sub_f32_e32 v75, v75, v149
	v_exp_f32_e32 v74, v74
	v_sub_f32_e32 v92, v92, v149
	v_exp_f32_e32 v91, v91
	v_sub_f32_e32 v76, v76, v149
	v_exp_f32_e32 v75, v75
	v_sub_f32_e32 v93, v93, v149
	v_exp_f32_e32 v92, v92
	v_sub_f32_e32 v77, v77, v149
	v_exp_f32_e32 v76, v76
	v_sub_f32_e32 v94, v94, v149
	v_exp_f32_e32 v93, v93
	v_sub_f32_e32 v78, v78, v149
	v_exp_f32_e32 v77, v77
	v_sub_f32_e32 v95, v95, v149
	v_exp_f32_e32 v94, v94
	v_sub_f32_e32 v79, v79, v149
	v_exp_f32_e32 v78, v78
	v_sub_f32_e32 v96, v96, v149
	v_exp_f32_e32 v95, v95
	v_sub_f32_e32 v80, v80, v149
	v_exp_f32_e32 v79, v79
	v_sub_f32_e32 v97, v97, v149
	v_exp_f32_e32 v96, v96
	v_sub_f32_e32 v81, v81, v149
	v_exp_f32_e32 v80, v80
	v_exp_f32_e32 v97, v97
	v_exp_f32_e32 v81, v81
	s_nop 0
	v_add_f32_e32 v180, v82, v83
	v_add_f32_e32 v181, v84, v85
	v_add_f32_e32 v182, v66, v67
	v_add_f32_e32 v120, v68, v69
	v_add_f32_e32 v180, v180, v86
	v_add_f32_e32 v181, v181, v87
	v_add_f32_e32 v182, v182, v70
	v_add_f32_e32 v120, v120, v71
	v_add_f32_e32 v180, v180, v88
	v_add_f32_e32 v181, v181, v89
	v_add_f32_e32 v182, v182, v72
	v_add_f32_e32 v120, v120, v73
	v_add_f32_e32 v180, v180, v90
	v_add_f32_e32 v181, v181, v91
	v_add_f32_e32 v182, v182, v74
	v_add_f32_e32 v120, v120, v75
	v_add_f32_e32 v180, v180, v92
	v_add_f32_e32 v181, v181, v93
	v_add_f32_e32 v182, v182, v76
	v_add_f32_e32 v120, v120, v77
	v_add_f32_e32 v180, v180, v94
	v_add_f32_e32 v181, v181, v95
	v_add_f32_e32 v182, v182, v78
	v_add_f32_e32 v120, v120, v79
	v_add_f32_e32 v180, v180, v96
	v_add_f32_e32 v181, v181, v97
	v_add_f32_e32 v182, v182, v80
	v_add_f32_e32 v120, v120, v81
	v_add_f32_e32 v180, v180, v181
	v_add_f32_e32 v182, v182, v120
	v_cvt_pk_bf16_f32 v202, v82, v83
	v_cvt_pk_bf16_f32 v203, v84, v85
	v_cvt_pk_bf16_f32 v204, v86, v87
	v_cvt_pk_bf16_f32 v205, v88, v89
	v_cvt_pk_bf16_f32 v206, v90, v91
	v_cvt_pk_bf16_f32 v207, v92, v93
	v_cvt_pk_bf16_f32 v208, v94, v95
	v_cvt_pk_bf16_f32 v209, v96, v97
	v_add_f32_e32 v180, v180, v182
	v_cvt_pk_bf16_f32 v210, v66, v67
	v_cvt_pk_bf16_f32 v211, v68, v69
	v_cvt_pk_bf16_f32 v212, v70, v71
	v_cvt_pk_bf16_f32 v213, v72, v73
	v_cvt_pk_bf16_f32 v214, v74, v75
	v_cvt_pk_bf16_f32 v215, v76, v77
	v_cvt_pk_bf16_f32 v216, v78, v79
	v_cvt_pk_bf16_f32 v217, v80, v81
	v_add_f32_e32 v150, v150, v180
	s_waitcnt lgkmcnt(0)
.Ldf_A_skip:
	s_cmp_eq_u32 s60, 0
	s_cbranch_scc1 .Ldf_a_done
	s_add_i32 s30, s37, 3
	s_cmp_lt_u32 s30, s63
	s_cbranch_scc1 .Ldf_a_w
	s_waitcnt vmcnt(0)
	s_branch .Ldf_a_done

; template <int DV, int NMAP>
; __device__ __forceinline__ void attn_unit(LAS unsigned char* lds, const bf16_t* U, bf16_t* MIX, const float* logf, int b, int h, int qb, float lam, float slope2, const float* gn, float outscale, const int tid) {
;     ...
;         if (t + 1 < NT) { if (PER == 2) asm volatile("s_waitcnt vmcnt(2)\n\ts_barrier" ::: "memory"); else asm volatile("s_waitcnt vmcnt(4)\n\ts_barrier" ::: "memory"); }
;         else asm volatile("s_waitcnt vmcnt(0)\n\ts_barrier" ::: "memory");
;         if (t + 2 < NT) AT_DMA(t + 2, st2);
.Ldf_a_done:
	s_cmp_eq_u32 s60, 0
	s_cbranch_scc1 .Ldf_nobarA
	s_barrier
.Ldf_nobarA:
	s_add_i32 s30, s37, 3
	s_add_i32 s30, s30, s60
	s_cmp_ge_u32 s30, s63
	s_cbranch_scc1 .Ldf_nodma
	s_and_b32 s30, s30, 3
	s_mul_i32 s31, s30, 0x4200
	s_add_i32 s31, s31, s64
	s_lshl_b32 s20, s30, 14
	s_add_i32 s20, s20, s66
	s_mov_b32 m0, s31
	v_lshl_add_u64 v[116:117], v[136:137], 0, s[24:25]
	global_load_lds_dwordx4 v[136:137], off
	s_add_i32 m0, s31, 0x2100
	v_lshl_add_u64 v[136:137], v[136:137], 0, s[28:29]
	global_load_lds_dwordx4 v[116:117], off
	s_mov_b32 m0, s20
	v_lshl_add_u64 v[116:117], v[138:139], 0, s[24:25]
	global_load_lds_dwordx4 v[138:139], off
	s_add_i32 m0, s20, 0x400
	v_lshl_add_u64 v[138:139], v[138:139], 0, s[28:29]
	global_load_lds_dwordx4 v[116:117], off

; template <int DV, int NMAP>
; __device__ __forceinline__ void attn_unit(LAS unsigned char* lds, const bf16_t* U, bf16_t* MIX, const float* logf, int b, int h, int qb, float lam, float slope2, const float* gn, float outscale, const int tid) {
;     ...
;     for (int t = 0; t < NT; ++t) {
;         if (t + 1 < NT) { if (PER == 2) asm volatile("s_waitcnt vmcnt(2)\n\ts_barrier" ::: "memory"); else asm volatile("s_waitcnt vmcnt(4)\n\ts_barrier" ::: "memory"); }
;         else asm volatile("s_waitcnt vmcnt(0)\n\ts_barrier" ::: "memory");
;         if (t + 2 < NT) AT_DMA(t + 2, st2);
.Ldf_B_end:
	s_cmp_lg_u32 s60, 0
	s_cbranch_scc1 .Ldf_b_done
	s_add_i32 s30, s37, 3
	s_cmp_lt_u32 s30, s63
	s_cbranch_scc1 .Ldf_b_w
	s_waitcnt vmcnt(0)
	s_branch .Ldf_b_done

; template <int DV, int NMAP>
; __device__ __forceinline__ void attn_unit(LAS unsigned char* lds, const bf16_t* U, bf16_t* MIX, const float* logf, int b, int h, int qb, float lam, float slope2, const float* gn, float outscale, const int tid) {
;     ...
;     for (int t = 0; t < NT; ++t) {
;     ...
;         st = (st == 2) ? 0 : st + 1; st2 = (st2 == 2) ? 0 : st2 + 1;
;     }
.Ldf_nobarB:
	s_add_i32 s37, s37, 1
	s_cmp_lt_u32 s37, s63
	s_cbranch_scc1 .Ldf_loop

; template <int DV, int NMAP>
; __device__ __forceinline__ void attn_unit(LAS unsigned char* lds, const bf16_t* U, bf16_t* MIX, const float* logf, int b, int h, int qb, float lam, float slope2, const float* gn, float outscale, const int tid) {
;     ...
;         if (map == 0) {
;             float ss = 0.f;
; #pragma unroll
;             for (int d = 0; d < NDB; ++d)
; #pragma unroll
;                 for (int r = 0; r < 16; ++r) { const float v = o[d][r] * inv - ex[(d * 16 + r) * 64]; o[d][r] = v; ss += v * v; }
;             ss += __shfl_xor(ss, 32);
;     ...
;                 for (int g = 0; g < 4; ++g) { const f32x4 gv = *(const f32x4*)(gn + 32 * d + 8 * g + 4 * hi);
.LBB0_231:
	s_cmpk_gt_u32 s33, 0xff
	s_waitcnt lgkmcnt(0)
	s_barrier
	s_cbranch_scc1 .LBB0_175
	global_load_dwordx4 v[80:83], v[132:133], off
	global_load_dwordx4 v[84:87], v[132:133], off offset:32
	global_load_dwordx4 v[88:91], v[132:133], off offset:64
	global_load_dwordx4 v[92:95], v[132:133], off offset:96
	global_load_dwordx4 v[96:99], v[132:133], off offset:128
	global_load_dwordx4 v[100:103], v[132:133], off offset:160
	global_load_dwordx4 v[104:107], v[132:133], off offset:192
	global_load_dwordx4 v[108:111], v[132:133], off offset:224
	global_load_dwordx4 v[112:115], v[132:133], off offset:256
	global_load_dwordx4 v[116:119], v[132:133], off offset:288
	global_load_dwordx4 v[152:155], v[132:133], off offset:320
	global_load_dwordx4 v[156:159], v[132:133], off offset:352
	global_load_dwordx4 v[160:163], v[132:133], off offset:384
	global_load_dwordx4 v[164:167], v[132:133], off offset:416
	global_load_dwordx4 v[168:171], v[132:133], off offset:448
	global_load_dwordx4 v[172:175], v[132:133], off offset:480
	ds_read2st64_b32 v[66:67], v77 offset0:33 offset1:34
	ds_read2st64_b32 v[68:69], v77 offset0:35 offset1:36
	ds_read2st64_b32 v[70:71], v77 offset0:53 offset1:54
	s_lshl_b32 s20, s27, 1
	s_waitcnt lgkmcnt(2)
	v_fma_f32 v66, v50, v0, -v66
	v_fma_f32 v50, v51, v0, -v67
	s_waitcnt lgkmcnt(1)
	v_fma_f32 v51, v52, v0, -v68
	v_fma_f32 v52, v53, v0, -v69
	ds_read2st64_b32 v[68:69], v77 offset0:37 offset1:38
	v_mul_f32_e32 v78, v50, v50
	v_fmac_f32_e32 v78, v66, v66
	v_fmac_f32_e32 v78, v51, v51
	v_fmac_f32_e32 v78, v52, v52
	s_waitcnt lgkmcnt(0)
	v_fma_f32 v53, v54, v0, -v68
	v_fma_f32 v54, v55, v0, -v69
	ds_read2st64_b32 v[68:69], v77 offset0:39 offset1:40
	v_fmac_f32_e32 v78, v53, v53
	v_fmac_f32_e32 v78, v54, v54
	s_waitcnt lgkmcnt(0)
	v_fma_f32 v55, v56, v0, -v68
	v_fma_f32 v56, v57, v0, -v69
	ds_read2st64_b32 v[68:69], v77 offset0:41 offset1:42
	v_fmac_f32_e32 v78, v55, v55
	v_fmac_f32_e32 v78, v56, v56
	s_waitcnt lgkmcnt(0)
	v_fma_f32 v58, v58, v0, -v68
	v_fma_f32 v57, v59, v0, -v69
	ds_read2st64_b32 v[68:69], v77 offset0:43 offset1:44
	v_fmac_f32_e32 v78, v58, v58
	v_fmac_f32_e32 v78, v57, v57
	s_waitcnt lgkmcnt(0)
	v_fma_f32 v67, v60, v0, -v68
	v_fma_f32 v60, v61, v0, -v69
	ds_read2st64_b32 v[68:69], v77 offset0:45 offset1:46
	v_fmac_f32_e32 v78, v67, v67
	v_fmac_f32_e32 v78, v60, v60
	s_waitcnt lgkmcnt(0)
	v_fma_f32 v61, v62, v0, -v68
	v_fma_f32 v59, v63, v0, -v69
	ds_read2st64_b32 v[62:63], v77 offset0:47 offset1:48
	v_fmac_f32_e32 v78, v61, v61
	v_fmac_f32_e32 v78, v59, v59
	s_waitcnt lgkmcnt(0)
	v_fma_f32 v68, v64, v0, -v62
	v_fma_f32 v63, v65, v0, -v63
	ds_read2st64_b32 v[64:65], v77 offset0:49 offset1:50
	v_fmac_f32_e32 v78, v68, v68
	v_fmac_f32_e32 v78, v63, v63
	s_waitcnt lgkmcnt(0)
	v_fma_f32 v62, v34, v0, -v64
	v_fma_f32 v34, v35, v0, -v65
	ds_read2st64_b32 v[64:65], v77 offset0:51 offset1:52
	v_fma_f32 v35, v39, v0, -v71
	v_fmac_f32_e32 v78, v62, v62
	v_fmac_f32_e32 v78, v34, v34
	s_waitcnt lgkmcnt(0)
	v_fma_f32 v64, v36, v0, -v64
	v_fma_f32 v36, v37, v0, -v65
	v_fma_f32 v37, v38, v0, -v70
	ds_read2st64_b32 v[38:39], v77 offset0:55 offset1:56
	v_fmac_f32_e32 v78, v64, v64
	v_fmac_f32_e32 v78, v36, v36
	v_fmac_f32_e32 v78, v37, v37
	v_fmac_f32_e32 v78, v35, v35
	s_waitcnt lgkmcnt(0)
	v_fma_f32 v69, v40, v0, -v38
	v_fma_f32 v65, v41, v0, -v39
	ds_read2st64_b32 v[40:41], v77 offset0:57 offset1:58
	v_fmac_f32_e32 v78, v69, v69
	v_fmac_f32_e32 v78, v65, v65
	s_waitcnt lgkmcnt(0)
	v_fma_f32 v39, v42, v0, -v40
	v_fma_f32 v38, v43, v0, -v41
	ds_read2st64_b32 v[40:41], v77 offset0:59 offset1:60
	v_fmac_f32_e32 v78, v39, v39
	v_fmac_f32_e32 v78, v38, v38
	s_waitcnt lgkmcnt(0)
	v_fma_f32 v43, v44, v0, -v40
	v_fma_f32 v41, v45, v0, -v41
	ds_read2st64_b32 v[44:45], v77 offset0:61 offset1:62
	v_fmac_f32_e32 v78, v43, v43
	v_fmac_f32_e32 v78, v41, v41
	s_waitcnt lgkmcnt(0)
	v_fma_f32 v42, v46, v0, -v44
	v_fma_f32 v40, v47, v0, -v45
	ds_read2st64_b32 v[44:45], v77 offset0:63 offset1:64
	v_fmac_f32_e32 v78, v42, v42
	v_fmac_f32_e32 v78, v40, v40
	s_waitcnt lgkmcnt(0)
	v_fma_f32 v47, v48, v0, -v44
	v_fma_f32 v45, v49, v0, -v45
	ds_read2st64_b32 v[48:49], v77 offset0:65 offset1:66
	v_fmac_f32_e32 v78, v47, v47
	v_fmac_f32_e32 v78, v45, v45
	s_waitcnt lgkmcnt(0)
	v_fma_f32 v44, v18, v0, -v48
	v_fma_f32 v18, v19, v0, -v49
	ds_read2st64_b32 v[48:49], v77 offset0:67 offset1:68
	v_fmac_f32_e32 v78, v44, v44
	v_fmac_f32_e32 v78, v18, v18
	s_waitcnt lgkmcnt(0)
	v_fma_f32 v46, v20, v0, -v48
	v_fma_f32 v20, v21, v0, -v49
	ds_read2st64_b32 v[48:49], v77 offset0:69 offset1:70
	v_fmac_f32_e32 v78, v46, v46
	v_fmac_f32_e32 v78, v20, v20
	s_waitcnt lgkmcnt(0)
	v_fma_f32 v21, v22, v0, -v48
	v_fma_f32 v19, v23, v0, -v49
	ds_read2st64_b32 v[22:23], v77 offset0:71 offset1:72
	v_fmac_f32_e32 v78, v21, v21
	v_fmac_f32_e32 v78, v19, v19
	s_waitcnt lgkmcnt(0)
	v_fma_f32 v49, v24, v0, -v22
	v_fma_f32 v48, v25, v0, -v23
	ds_read2st64_b32 v[24:25], v77 offset0:73 offset1:74
	v_fmac_f32_e32 v78, v49, v49
	v_fmac_f32_e32 v78, v48, v48
	s_waitcnt lgkmcnt(0)
	v_fma_f32 v23, v26, v0, -v24
	v_fma_f32 v22, v27, v0, -v25
	ds_read2st64_b32 v[24:25], v77 offset0:75 offset1:76
	ds_read2st64_b32 v[26:27], v77 offset0:77 offset1:78
	v_fmac_f32_e32 v78, v23, v23
	v_fmac_f32_e32 v78, v22, v22
	s_waitcnt lgkmcnt(1)
	v_fma_f32 v28, v28, v0, -v24
	s_waitcnt lgkmcnt(0)
	v_fma_f32 v26, v30, v0, -v26
	v_fma_f32 v24, v31, v0, -v27
	ds_read2st64_b32 v[30:31], v77 offset0:79 offset1:80
	v_fmac_f32_e32 v78, v28, v28
	v_fma_f32 v25, v29, v0, -v25
	v_fmac_f32_e32 v78, v25, v25
	v_fmac_f32_e32 v78, v26, v26
	s_waitcnt lgkmcnt(0)
; __device__ __forceinline__ unsigned pk_bf16(float lo, float hi) { return pg8::cvt_pk_bf16(lo, hi); }
; template <int DV, int NMAP>
; __device__ __forceinline__ void attn_unit(LAS unsigned char* lds, const bf16_t* U, bf16_t* MIX, const float* logf, int b, int h, int qb, float lam, float slope2, const float* gn, float outscale, const int tid) {
;     ...
;                 for (int r = 0; r < 16; ++r) { const float v = o[d][r] * inv - ex[(d * 16 + r) * 64]; o[d][r] = v; ss += v * v; }
;             ss += __shfl_xor(ss, 32);
;             const float rn = outscale / sqrtf(ss * (1.0f / 128.0f) + EPS);
; #pragma unroll
;             for (int d = 0; d < NDB; ++d)
; #pragma unroll
;                 for (int g = 0; g < 4; ++g) { const f32x4 gv = *(const f32x4*)(gn + 32 * d + 8 * g + 4 * hi);
;                     u32x2 w; w.x = pk_bf16(o[d][4 * g] * rn * gv[0], o[d][4 * g + 1] * rn * gv[1]); w.y = pk_bf16(o[d][4 * g + 2] * rn * gv[2], o[d][4 * g + 3] * rn * gv[3]);
;                     *(u32x2*)(MIX + orow + 512 + 128 * h + 32 * d + 8 * g + 4 * hi) = w; }
	v_fma_f32 v76, v32, v0, -v30
	v_fma_f32 v74, v33, v0, -v31
	ds_read2st64_b32 v[30:31], v77 offset0:81 offset1:82
	v_fmac_f32_e32 v78, v24, v24
	v_fmac_f32_e32 v78, v76, v76
	v_fmac_f32_e32 v78, v74, v74
	s_waitcnt lgkmcnt(0)
	v_fma_f32 v32, v2, v0, -v30
	v_fma_f32 v31, v3, v0, -v31
	ds_read2st64_b32 v[2:3], v77 offset0:83 offset1:84
	v_fmac_f32_e32 v78, v32, v32
	v_fmac_f32_e32 v78, v31, v31
	s_waitcnt lgkmcnt(0)
	v_fma_f32 v75, v4, v0, -v2
	v_fma_f32 v72, v5, v0, -v3
	ds_read2st64_b32 v[2:3], v77 offset0:85 offset1:86
	v_fmac_f32_e32 v78, v75, v75
	v_fmac_f32_e32 v78, v72, v72
	s_waitcnt lgkmcnt(0)
	v_fma_f32 v73, v6, v0, -v2
	v_fma_f32 v70, v7, v0, -v3
	ds_read2st64_b32 v[2:3], v77 offset0:87 offset1:88
	v_fmac_f32_e32 v78, v73, v73
	v_fmac_f32_e32 v78, v70, v70
	s_waitcnt lgkmcnt(0)
	v_fma_f32 v71, v8, v0, -v2
	v_fma_f32 v33, v9, v0, -v3
	ds_read2st64_b32 v[2:3], v77 offset0:89 offset1:90
	v_fmac_f32_e32 v78, v71, v71
	v_fmac_f32_e32 v78, v33, v33
	s_waitcnt lgkmcnt(0)
	v_fma_f32 v30, v10, v0, -v2
	v_fma_f32 v29, v11, v0, -v3
	ds_read2st64_b32 v[2:3], v77 offset0:91 offset1:92
	v_fmac_f32_e32 v78, v30, v30
	v_fmac_f32_e32 v78, v29, v29
	s_waitcnt lgkmcnt(0)
	v_fma_f32 v27, v12, v0, -v2
	v_fma_f32 v13, v13, v0, -v3
	ds_read2st64_b32 v[2:3], v77 offset0:93 offset1:94
	v_fmac_f32_e32 v78, v27, v27
	v_fmac_f32_e32 v78, v13, v13
	s_waitcnt lgkmcnt(0)
	v_pk_fma_f32 v[8:9], v[14:15], v[0:1], v[2:3] op_sel_hi:[1,0,1] neg_lo:[0,0,1] neg_hi:[0,0,1]
	s_nop 0
	v_pk_mul_f32 v[2:3], v[8:9], v[8:9]
	s_nop 0
	v_add_f32_e32 v2, v78, v2
	v_add_f32_e32 v4, v2, v3
	ds_read2st64_b32 v[2:3], v77 offset0:95 offset1:96
	s_waitcnt lgkmcnt(0)
	v_pk_fma_f32 v[6:7], v[16:17], v[0:1], v[2:3] op_sel_hi:[1,0,1] neg_lo:[0,0,1] neg_hi:[0,0,1]
	s_nop 0
	v_pk_mul_f32 v[2:3], v[6:7], v[6:7]
	s_nop 0
	v_add_f32_e32 v0, v4, v2
	v_add_f32_e32 v0, v0, v3
	ds_bpermute_b32 v2, v224, v0
	s_waitcnt lgkmcnt(0)
	v_add_f32_e32 v0, v0, v2
	v_fmamk_f32 v0, v0, 0x3c000000, v225
	v_cmp_gt_f32_e64 s[40:41], s16, v0
	v_mul_f32_e32 v2, 0x4f800000, v0
	s_nop 0
	v_cndmask_b32_e64 v0, v0, v2, s[40:41]
	v_sqrt_f32_e32 v2, v0
	s_nop 0
	v_add_u32_e32 v3, -1, v2
	v_fma_f32 v4, -v3, v2, v0
	v_cmp_ge_f32_e32 vcc, 0, v4
	v_add_u32_e32 v4, 1, v2
	s_nop 0
	v_cndmask_b32_e32 v3, v2, v3, vcc
	v_fma_f32 v2, -v4, v2, v0
	v_cmp_lt_f32_e32 vcc, 0, v2
	s_nop 1
	v_cndmask_b32_e32 v2, v3, v4, vcc
	v_mul_f32_e32 v3, 0x37800000, v2
	v_cndmask_b32_e64 v2, v2, v3, s[40:41]
	v_cmp_class_f32_e32 vcc, v0, v226
	s_nop 1
	v_cndmask_b32_e32 v0, v2, v0, vcc
	v_div_scale_f32 v2, s[30:31], v0, v0, v144
	v_rcp_f32_e32 v3, v2
	v_readlane_b32 s30, v250, 34
	v_readlane_b32 s31, v250, 35
	v_fma_f32 v4, -v2, v3, 1.0
	v_fmac_f32_e32 v3, v4, v3
	v_div_scale_f32 v4, vcc, v144, v0, v144
	v_mul_f32_e32 v5, v4, v3
	v_fma_f32 v10, -v2, v5, v4
	v_fmac_f32_e32 v5, v10, v3
	v_fma_f32 v2, -v2, v5, v4
	v_div_fmas_f32 v2, v2, v3, v5
	v_div_fixup_f32 v12, v2, v0, v144
	v_lshlrev_b32_e32 v0, 11, v147
	v_lshl_add_u64 v[2:3], s[30:31], 0, v[0:1]
	v_lshl_add_u64 v[2:3], v[2:3], 0, s[20:21]
	v_lshlrev_b32_e32 v0, 1, v130
	v_lshl_add_u64 v[10:11], v[2:3], 0, v[0:1]
	s_waitcnt vmcnt(0)
; __device__ __forceinline__ unsigned pk_bf16(float lo, float hi) { return pg8::cvt_pk_bf16(lo, hi); }
; template <int DV, int NMAP>
; __device__ __forceinline__ void attn_unit(LAS unsigned char* lds, const bf16_t* U, bf16_t* MIX, const float* logf, int b, int h, int qb, float lam, float slope2, const float* gn, float outscale, const int tid) {
;     ...
; #pragma unroll
;             for (int d = 0; d < NDB; ++d)
; #pragma unroll
;                 for (int g = 0; g < 4; ++g) { const f32x4 gv = *(const f32x4*)(gn + 32 * d + 8 * g + 4 * hi);
;                     u32x2 w; w.x = pk_bf16(o[d][4 * g] * rn * gv[0], o[d][4 * g + 1] * rn * gv[1]); w.y = pk_bf16(o[d][4 * g + 2] * rn * gv[2], o[d][4 * g + 3] * rn * gv[3]);
;                     *(u32x2*)(MIX + orow + 512 + 128 * h + 32 * d + 8 * g + 4 * hi) = w; }
	v_mov_b32_e32 v2, v80
	v_mov_b32_e32 v3, v81
	v_mov_b32_e32 v4, v82
	v_mov_b32_e32 v5, v83
	v_mul_f32_e32 v0, v66, v12
	v_mul_f32_e32 v0, v2, v0
	v_mul_f32_e32 v2, v50, v12
	v_mul_f32_e32 v2, v3, v2
	v_mul_f32_e32 v3, v52, v12
	v_cvt_pk_bf16_f32 v2, v0, v2
	v_mul_f32_e32 v0, v51, v12
	v_mul_f32_e32 v3, v5, v3
	v_mul_f32_e32 v0, v4, v0
	v_cvt_pk_bf16_f32 v3, v0, v3
	global_store_dwordx2 v[10:11], v[2:3], off offset:1024
	v_mov_b32_e32 v2, v84
	v_mov_b32_e32 v3, v85
	v_mov_b32_e32 v4, v86
	v_mov_b32_e32 v5, v87
	v_mul_f32_e32 v0, v53, v12
	v_mul_f32_e32 v0, v2, v0
	v_mul_f32_e32 v2, v54, v12
	v_mul_f32_e32 v2, v3, v2
	v_mul_f32_e32 v3, v56, v12
	v_cvt_pk_bf16_f32 v2, v0, v2
	v_mul_f32_e32 v0, v55, v12
	v_mul_f32_e32 v3, v5, v3
	v_mul_f32_e32 v0, v4, v0
	v_cvt_pk_bf16_f32 v3, v0, v3
	global_store_dwordx2 v[10:11], v[2:3], off offset:1040
	v_mov_b32_e32 v2, v88
	v_mov_b32_e32 v3, v89
	v_mov_b32_e32 v4, v90
	v_mov_b32_e32 v5, v91
	v_mul_f32_e32 v0, v58, v12
	v_mul_f32_e32 v0, v0, v2
	v_mul_f32_e32 v2, v57, v12
	v_mul_f32_e32 v2, v2, v3
	v_mul_f32_e32 v3, v60, v12
	v_cvt_pk_bf16_f32 v2, v0, v2
	v_mul_f32_e32 v0, v67, v12
	v_mul_f32_e32 v3, v3, v5
	v_mul_f32_e32 v0, v0, v4
	v_cvt_pk_bf16_f32 v3, v0, v3
	global_store_dwordx2 v[10:11], v[2:3], off offset:1056
	v_mov_b32_e32 v2, v92
	v_mov_b32_e32 v3, v93
	v_mov_b32_e32 v4, v94
	v_mov_b32_e32 v5, v95
	v_mul_f32_e32 v0, v61, v12
	v_mul_f32_e32 v0, v0, v2
	v_mul_f32_e32 v2, v59, v12
	v_mul_f32_e32 v2, v2, v3
	v_mul_f32_e32 v3, v63, v12
	v_cvt_pk_bf16_f32 v2, v0, v2
	v_mul_f32_e32 v0, v68, v12
	v_mul_f32_e32 v3, v3, v5
	v_mul_f32_e32 v0, v0, v4
	v_cvt_pk_bf16_f32 v3, v0, v3
	global_store_dwordx2 v[10:11], v[2:3], off offset:1072
	v_mov_b32_e32 v2, v96
	v_mov_b32_e32 v3, v97
	v_mov_b32_e32 v4, v98
	v_mov_b32_e32 v5, v99
	v_mul_f32_e32 v0, v62, v12
	v_mul_f32_e32 v0, v0, v2
	v_mul_f32_e32 v2, v34, v12
	v_mul_f32_e32 v2, v2, v3
	v_mul_f32_e32 v3, v36, v12
	v_cvt_pk_bf16_f32 v2, v0, v2
	v_mul_f32_e32 v0, v64, v12
	v_mul_f32_e32 v3, v3, v5
	v_mul_f32_e32 v0, v0, v4
	v_cvt_pk_bf16_f32 v3, v0, v3
	global_store_dwordx2 v[10:11], v[2:3], off offset:1088
	v_mov_b32_e32 v2, v100
	v_mov_b32_e32 v3, v101
	v_mov_b32_e32 v4, v102
	v_mov_b32_e32 v5, v103
	v_mul_f32_e32 v0, v37, v12
	v_mul_f32_e32 v0, v0, v2
	v_mul_f32_e32 v2, v35, v12
	v_mul_f32_e32 v2, v2, v3
	v_mul_f32_e32 v3, v65, v12
	v_cvt_pk_bf16_f32 v2, v0, v2
	v_mul_f32_e32 v0, v69, v12
	v_mul_f32_e32 v3, v3, v5
	v_mul_f32_e32 v0, v0, v4
	v_cvt_pk_bf16_f32 v3, v0, v3
	global_store_dwordx2 v[10:11], v[2:3], off offset:1104
	v_mov_b32_e32 v2, v104
	v_mov_b32_e32 v3, v105
	v_mov_b32_e32 v4, v106
	v_mov_b32_e32 v5, v107
	v_mul_f32_e32 v0, v39, v12
	v_mul_f32_e32 v0, v0, v2
	v_mul_f32_e32 v2, v38, v12
	v_mul_f32_e32 v2, v2, v3
	v_mul_f32_e32 v3, v41, v12
	v_cvt_pk_bf16_f32 v2, v0, v2
	v_mul_f32_e32 v0, v43, v12
	v_mul_f32_e32 v3, v3, v5
	v_mul_f32_e32 v0, v0, v4
	v_cvt_pk_bf16_f32 v3, v0, v3
	global_store_dwordx2 v[10:11], v[2:3], off offset:1120
	v_mov_b32_e32 v2, v108
	v_mov_b32_e32 v3, v109
	v_mov_b32_e32 v4, v110
	v_mov_b32_e32 v5, v111
	v_mul_f32_e32 v0, v42, v12
	v_mul_f32_e32 v0, v0, v2
	v_mul_f32_e32 v2, v40, v12
	v_mul_f32_e32 v2, v2, v3
	v_mul_f32_e32 v3, v45, v12
	v_cvt_pk_bf16_f32 v2, v0, v2
	v_mul_f32_e32 v0, v47, v12
	v_mul_f32_e32 v3, v3, v5
	v_mul_f32_e32 v0, v0, v4
	v_cvt_pk_bf16_f32 v3, v0, v3
	global_store_dwordx2 v[10:11], v[2:3], off offset:1136
	v_mov_b32_e32 v2, v112
	v_mov_b32_e32 v3, v113
	v_mov_b32_e32 v4, v114
	v_mov_b32_e32 v5, v115
	v_mul_f32_e32 v0, v44, v12
	v_mul_f32_e32 v0, v0, v2
	v_mul_f32_e32 v2, v18, v12
	v_mul_f32_e32 v2, v2, v3
	v_mul_f32_e32 v3, v20, v12
	v_cvt_pk_bf16_f32 v2, v0, v2
	v_mul_f32_e32 v0, v46, v12
	v_mul_f32_e32 v3, v3, v5
	v_mul_f32_e32 v0, v0, v4
	v_cvt_pk_bf16_f32 v3, v0, v3
	global_store_dwordx2 v[10:11], v[2:3], off offset:1152
	v_mov_b32_e32 v2, v116
	v_mov_b32_e32 v3, v117
	v_mov_b32_e32 v4, v118
	v_mov_b32_e32 v5, v119
	v_mul_f32_e32 v0, v21, v12
	v_mul_f32_e32 v0, v0, v2
	v_mul_f32_e32 v2, v19, v12
	v_mul_f32_e32 v2, v2, v3
	v_mul_f32_e32 v3, v48, v12
	v_cvt_pk_bf16_f32 v2, v0, v2
	v_mul_f32_e32 v0, v49, v12
	v_mul_f32_e32 v3, v3, v5
	v_mul_f32_e32 v0, v0, v4
	v_cvt_pk_bf16_f32 v3, v0, v3
	global_store_dwordx2 v[10:11], v[2:3], off offset:1168
	v_mov_b32_e32 v2, v152
	v_mov_b32_e32 v3, v153
	v_mov_b32_e32 v4, v154
	v_mov_b32_e32 v5, v155
	v_mul_f32_e32 v0, v23, v12
	v_mul_f32_e32 v0, v0, v2
	v_mul_f32_e32 v2, v22, v12
	v_mul_f32_e32 v2, v2, v3
	v_mul_f32_e32 v3, v25, v12
	v_cvt_pk_bf16_f32 v2, v0, v2
	v_mul_f32_e32 v0, v28, v12
	v_mul_f32_e32 v3, v3, v5
	v_mul_f32_e32 v0, v0, v4
	v_cvt_pk_bf16_f32 v3, v0, v3
	global_store_dwordx2 v[10:11], v[2:3], off offset:1184
	v_mov_b32_e32 v2, v156
	v_mov_b32_e32 v3, v157
	v_mov_b32_e32 v4, v158
	v_mov_b32_e32 v5, v159
	v_mul_f32_e32 v0, v26, v12
	v_mul_f32_e32 v0, v0, v2
	v_mul_f32_e32 v2, v24, v12
	v_mul_f32_e32 v2, v2, v3
	v_mul_f32_e32 v3, v74, v12
	v_cvt_pk_bf16_f32 v2, v0, v2
	v_mul_f32_e32 v0, v76, v12
	v_mul_f32_e32 v3, v3, v5
	v_mul_f32_e32 v0, v0, v4
	v_cvt_pk_bf16_f32 v3, v0, v3
	global_store_dwordx2 v[10:11], v[2:3], off offset:1200
	v_mov_b32_e32 v2, v160
	v_mov_b32_e32 v3, v161
	v_mov_b32_e32 v4, v162
	v_mov_b32_e32 v5, v163
	v_mul_f32_e32 v0, v32, v12
	v_mul_f32_e32 v0, v0, v2
	v_mul_f32_e32 v2, v31, v12
	v_mul_f32_e32 v2, v2, v3
	v_mul_f32_e32 v3, v72, v12
	v_cvt_pk_bf16_f32 v2, v0, v2
	v_mul_f32_e32 v0, v75, v12
	v_mul_f32_e32 v3, v3, v5
	v_mul_f32_e32 v0, v0, v4
	v_cvt_pk_bf16_f32 v3, v0, v3
	global_store_dwordx2 v[10:11], v[2:3], off offset:1216
	v_mov_b32_e32 v2, v164
	v_mov_b32_e32 v3, v165
	v_mov_b32_e32 v4, v166
	v_mov_b32_e32 v5, v167
	v_mul_f32_e32 v0, v73, v12
	v_mul_f32_e32 v0, v0, v2
	v_mul_f32_e32 v2, v70, v12
	v_mul_f32_e32 v2, v2, v3
	v_mul_f32_e32 v3, v33, v12
	v_cvt_pk_bf16_f32 v2, v0, v2
	v_mul_f32_e32 v0, v71, v12
	v_mul_f32_e32 v3, v3, v5
	v_mul_f32_e32 v0, v0, v4
	v_cvt_pk_bf16_f32 v3, v0, v3
	global_store_dwordx2 v[10:11], v[2:3], off offset:1232
	v_mov_b32_e32 v2, v168
	v_mov_b32_e32 v3, v169
	v_mov_b32_e32 v4, v170
	v_mov_b32_e32 v5, v171
	v_mul_f32_e32 v0, v30, v12
	v_mul_f32_e32 v0, v0, v2
	v_mul_f32_e32 v2, v29, v12
	v_mul_f32_e32 v2, v2, v3
	v_mul_f32_e32 v3, v13, v12
	v_cvt_pk_bf16_f32 v2, v0, v2
	v_mul_f32_e32 v0, v27, v12
	v_mul_f32_e32 v3, v3, v5
	v_mul_f32_e32 v0, v0, v4
	v_cvt_pk_bf16_f32 v3, v0, v3
	global_store_dwordx2 v[10:11], v[2:3], off offset:1248
	v_mov_b32_e32 v2, v172
	v_mov_b32_e32 v3, v173
	v_mov_b32_e32 v4, v174
	v_mov_b32_e32 v5, v175
	v_mul_f32_e32 v0, v8, v12
	v_mul_f32_e32 v0, v0, v2
	v_mul_f32_e32 v2, v9, v12
	v_mul_f32_e32 v2, v2, v3
	v_mul_f32_e32 v3, v7, v12
	v_cvt_pk_bf16_f32 v2, v0, v2
	v_mul_f32_e32 v0, v6, v12
	v_mul_f32_e32 v3, v3, v5
	v_mul_f32_e32 v0, v0, v4
	v_cvt_pk_bf16_f32 v3, v0, v3
	global_store_dwordx2 v[10:11], v[2:3], off offset:1264
	s_branch .LBB0_175
